# v25: v24 + DMA-before-reads order also in P8 ph1/ph3 and P2a load segments (re-evaluated with in-situ phase timer)
# baseline (speedup 1.0000x reference)
; #define PG8_STAGE(bufoff, gbase, voff) do { _Pragma("unroll") for (int _i = 0; _i < 2; ++_i) \
;         __builtin_amdgcn_global_load_lds((const unsigned*)((const char*)(gbase) + (voff)[_i]), (LAS unsigned*)(lds + (bufoff) + ldsw + _i * 8192), 16, 0, 0); } while (0)
; #define PG8_LDA(dst, b, h) do { _Pragma("unroll") for (int m = 0; m < 4; ++m) _Pragma("unroll") for (int k = 0; k < 2; ++k) dst[m][k] = *(const LAS bf16x8*)(lds + PG8_SA(b, h) + aoff + m * 2048 + k * 1024); } while (0)
; #define PG8_LDB(dst, b, h) do { _Pragma("unroll") for (int n = 0; n < 2; ++n) _Pragma("unroll") for (int k = 0; k < 2; ++k) dst[n][k] = *(const LAS bf16x8*)(lds + PG8_SB(b, h) + boff + n * 2048 + k * 1024); } while (0)
; #define PG8_MMA(ai, bj, At, Bt) do { __builtin_amdgcn_s_setprio(1); _Pragma("unroll") for (int m = 0; m < 4; ++m) _Pragma("unroll") for (int n = 0; n < 2; ++n) _Pragma("unroll") for (int k = 0; k < 2; ++k) \
;         acc[ai][bj][m][n] = __builtin_amdgcn_mfma_f32_16x16x32_bf16(Bt[n][k], At[m][k], acc[ai][bj][m][n], 0, 0, 0); __builtin_amdgcn_s_setprio(0); } while (0)
; #define PG8_WAIT_V(n) asm volatile("s_waitcnt vmcnt(" #n ")" ::: "memory")
; #define PG8_WAIT_L(n) asm volatile("s_waitcnt lgkmcnt(" #n ")" ::: "memory")
; #define PG8_BAR __builtin_amdgcn_s_barrier()
; #define PG8_SCHED __builtin_amdgcn_sched_barrier(0)
; template <class Epi, class Sched, bool ALIGN_EPI, bool SP2>
; __device__ __forceinline__ void gemm_phase(LAS unsigned char* lds, const Gemm g, const Sched& S, const Epi& E) {
;     ...
;             const char* a1 = cA + (size_t)(t + 1) * kstep;
;             const char* a2 = last ? nA : cA + (size_t)(t + 2) * kstep; const char* b2 = last ? nB : cB + (size_t)(t + 2) * kstep;
;             const char* a3 = a2 + kstep; const char* b3 = b2 + kstep;
;             if constexpr (SP2) {
;             PG8_LDB(B0, 0, 0); PG8_LDB(B1, 0, 1); PG8_SCHED; PG8_LDA(At, 0, 0); PG8_STAGE(PG8_SA(1, 1), a1 + hstep, voffA);
;             PG8_WAIT_V(8); PG8_WAIT_L(0); PG8_BAR; PG8_MMA(0, 0, At, B0); PG8_MMA(0, 1, At, B1); PG8_BAR; PG8_SCHED;
;             PG8_LDA(At, 0, 1); PG8_STAGE(PG8_SB(0, 0), b2, voffB); PG8_STAGE(PG8_SB(0, 1), b2 + hstep, voffB); PG8_STAGE(PG8_SA(0, 0), a2, voffA);
;             PG8_WAIT_V(8); PG8_WAIT_L(0); PG8_BAR; PG8_MMA(1, 0, At, B0); PG8_MMA(1, 1, At, B1); PG8_BAR; PG8_SCHED;
.LBB0_216:
	s_add_u32 s8, s6, 0xfffc0080
	s_addc_u32 s9, s7, -1
	s_cmp_eq_u32 s43, 12
	s_cselect_b32 s11, s2, s9
	s_cselect_b32 s10, s3, s8
	s_cselect_b32 s9, s5, s42
	s_cselect_b32 s8, s12, s13
	s_add_i32 m0, s71, 0xc000
	s_nop 0
	global_load_lds_dwordx4 v160, s[6:7]
	s_add_i32 m0, s71, 0xe000
	s_nop 0
	global_load_lds_dwordx4 v162, s[6:7]
	ds_read_b128 v[128:131], v177
	ds_read_b128 v[132:135], v177 offset:1024
	ds_read_b128 v[136:139], v177 offset:2048
	ds_read_b128 v[140:143], v177 offset:3072
	ds_read_b128 v[168:171], v178
	ds_read_b128 v[184:187], v178 offset:1024
	ds_read_b128 v[188:191], v178 offset:2048
	ds_read_b128 v[192:195], v178 offset:3072
	ds_read_b128 v[196:199], v179
	ds_read_b128 v[200:203], v179 offset:1024
	ds_read_b128 v[204:207], v179 offset:2048
	ds_read_b128 v[208:211], v179 offset:3072
	ds_read_b128 v[212:215], v179 offset:4096
	ds_read_b128 v[216:219], v179 offset:5120
	ds_read_b128 v[220:223], v179 offset:6144
	ds_read_b128 v[224:227], v179 offset:7168
	s_waitcnt vmcnt(8)
	s_waitcnt lgkmcnt(0)
	s_barrier
	s_setprio 1
	s_waitcnt lgkmcnt(0)
	v_mfma_f32_16x16x32_bf16 v[124:127], v[128:131], v[196:199], v[124:127]
	v_mfma_f32_16x16x32_bf16 v[120:123], v[136:139], v[196:199], v[120:123]
	v_mfma_f32_16x16x32_bf16 v[116:119], v[128:131], v[204:207], v[116:119]
	v_mfma_f32_16x16x32_bf16 v[112:115], v[136:139], v[204:207], v[112:115]
	v_mfma_f32_16x16x32_bf16 v[108:111], v[128:131], v[212:215], v[108:111]
	v_mfma_f32_16x16x32_bf16 v[104:107], v[136:139], v[212:215], v[104:107]
	v_mfma_f32_16x16x32_bf16 v[100:103], v[128:131], v[220:223], v[100:103]
	v_mfma_f32_16x16x32_bf16 v[96:99], v[136:139], v[220:223], v[96:99]
	v_mfma_f32_16x16x32_bf16 v[124:127], v[132:135], v[200:203], v[124:127]
	v_mfma_f32_16x16x32_bf16 v[120:123], v[140:143], v[200:203], v[120:123]
	v_mfma_f32_16x16x32_bf16 v[116:119], v[132:135], v[208:211], v[116:119]
	v_mfma_f32_16x16x32_bf16 v[112:115], v[140:143], v[208:211], v[112:115]
	v_mfma_f32_16x16x32_bf16 v[108:111], v[132:135], v[216:219], v[108:111]
	v_mfma_f32_16x16x32_bf16 v[104:107], v[140:143], v[216:219], v[104:107]
	v_mfma_f32_16x16x32_bf16 v[100:103], v[132:135], v[224:227], v[100:103]
	v_mfma_f32_16x16x32_bf16 v[96:99], v[140:143], v[224:227], v[96:99]
	s_setprio 0
	s_setprio 1
	v_mfma_f32_16x16x32_bf16 v[60:63], v[168:171], v[196:199], v[60:63]
	v_mfma_f32_16x16x32_bf16 v[56:59], v[188:191], v[196:199], v[56:59]
	v_mfma_f32_16x16x32_bf16 v[52:55], v[168:171], v[204:207], v[52:55]
	v_mfma_f32_16x16x32_bf16 v[48:51], v[188:191], v[204:207], v[48:51]
	v_mfma_f32_16x16x32_bf16 v[44:47], v[168:171], v[212:215], v[44:47]
	v_mfma_f32_16x16x32_bf16 v[40:43], v[188:191], v[212:215], v[40:43]
	v_mfma_f32_16x16x32_bf16 v[36:39], v[168:171], v[220:223], v[36:39]
	v_mfma_f32_16x16x32_bf16 v[32:35], v[188:191], v[220:223], v[32:35]
	v_mfma_f32_16x16x32_bf16 v[60:63], v[184:187], v[200:203], v[60:63]
	v_mfma_f32_16x16x32_bf16 v[56:59], v[192:195], v[200:203], v[56:59]
	v_mfma_f32_16x16x32_bf16 v[52:55], v[184:187], v[208:211], v[52:55]
	v_mfma_f32_16x16x32_bf16 v[48:51], v[192:195], v[208:211], v[48:51]
	v_mfma_f32_16x16x32_bf16 v[44:47], v[184:187], v[216:219], v[44:47]
	v_mfma_f32_16x16x32_bf16 v[40:43], v[192:195], v[216:219], v[40:43]
	v_mfma_f32_16x16x32_bf16 v[36:39], v[184:187], v[224:227], v[36:39]
	v_mfma_f32_16x16x32_bf16 v[32:35], v[192:195], v[224:227], v[32:35]
	s_setprio 0
	s_barrier
	s_add_i32 s44, s74, s70
	s_mov_b32 m0, s44
	s_nop 0
	global_load_lds_dwordx4 v146, s[8:9]
	s_add_i32 m0, s44, 0x2000
	s_add_u32 s44, s8, 0x40000
	s_addc_u32 s45, s9, 0
	s_add_i32 s50, s75, s70
	global_load_lds_dwordx4 v150, s[8:9]
	s_mov_b32 m0, s50
	s_nop 0
	global_load_lds_dwordx4 v146, s[44:45]
	s_add_i32 m0, s50, 0x2000
	s_nop 0
	global_load_lds_dwordx4 v150, s[44:45]
	s_mov_b32 m0, s71
	s_nop 0
	global_load_lds_dwordx4 v144, s[10:11]
	s_mov_b32 m0, s72
	s_nop 0
	global_load_lds_dwordx4 v148, s[10:11]
	ds_read_b128 v[196:199], v179 offset:16384
	ds_read_b128 v[200:203], v179 offset:17408
	ds_read_b128 v[204:207], v179 offset:18432
	ds_read_b128 v[208:211], v179 offset:19456
	ds_read_b128 v[212:215], v179 offset:20480
	ds_read_b128 v[216:219], v179 offset:21504
	ds_read_b128 v[220:223], v179 offset:22528
	ds_read_b128 v[224:227], v179 offset:23552
	s_waitcnt vmcnt(8)
	s_waitcnt lgkmcnt(0)
	s_barrier
	s_setprio 1
	s_waitcnt lgkmcnt(0)
	v_mfma_f32_16x16x32_bf16 v[92:95], v[128:131], v[196:199], v[92:95]
	v_mfma_f32_16x16x32_bf16 v[88:91], v[136:139], v[196:199], v[88:91]
	v_mfma_f32_16x16x32_bf16 v[84:87], v[128:131], v[204:207], v[84:87]
	v_mfma_f32_16x16x32_bf16 v[80:83], v[136:139], v[204:207], v[80:83]
	v_mfma_f32_16x16x32_bf16 v[76:79], v[128:131], v[212:215], v[76:79]
	v_mfma_f32_16x16x32_bf16 v[72:75], v[136:139], v[212:215], v[72:75]
	v_mfma_f32_16x16x32_bf16 v[68:71], v[128:131], v[220:223], v[68:71]
	v_mfma_f32_16x16x32_bf16 v[64:67], v[136:139], v[220:223], v[64:67]
	v_mfma_f32_16x16x32_bf16 v[92:95], v[132:135], v[200:203], v[92:95]
	v_mfma_f32_16x16x32_bf16 v[88:91], v[140:143], v[200:203], v[88:91]
	v_mfma_f32_16x16x32_bf16 v[84:87], v[132:135], v[208:211], v[84:87]
	v_mfma_f32_16x16x32_bf16 v[80:83], v[140:143], v[208:211], v[80:83]
	v_mfma_f32_16x16x32_bf16 v[76:79], v[132:135], v[216:219], v[76:79]
	v_mfma_f32_16x16x32_bf16 v[72:75], v[140:143], v[216:219], v[72:75]
	v_mfma_f32_16x16x32_bf16 v[68:71], v[132:135], v[224:227], v[68:71]
	v_mfma_f32_16x16x32_bf16 v[64:67], v[140:143], v[224:227], v[64:67]
	s_setprio 0
	s_setprio 1
	v_mfma_f32_16x16x32_bf16 v[28:31], v[168:171], v[196:199], v[28:31]
	v_mfma_f32_16x16x32_bf16 v[24:27], v[188:191], v[196:199], v[24:27]
	v_mfma_f32_16x16x32_bf16 v[20:23], v[168:171], v[204:207], v[20:23]
	v_mfma_f32_16x16x32_bf16 v[16:19], v[188:191], v[204:207], v[16:19]
	v_mfma_f32_16x16x32_bf16 v[12:15], v[168:171], v[212:215], v[12:15]
	v_mfma_f32_16x16x32_bf16 v[8:11], v[188:191], v[212:215], v[8:11]
	v_mfma_f32_16x16x32_bf16 v[4:7], v[168:171], v[220:223], v[4:7]
	v_mfma_f32_16x16x32_bf16 v[0:3], v[188:191], v[220:223], v[0:3]
	v_mfma_f32_16x16x32_bf16 v[28:31], v[184:187], v[200:203], v[28:31]
	v_mfma_f32_16x16x32_bf16 v[24:27], v[192:195], v[200:203], v[24:27]
	v_mfma_f32_16x16x32_bf16 v[20:23], v[184:187], v[208:211], v[20:23]
	v_mfma_f32_16x16x32_bf16 v[16:19], v[192:195], v[208:211], v[16:19]
	v_mfma_f32_16x16x32_bf16 v[12:15], v[184:187], v[216:219], v[12:15]
	v_mfma_f32_16x16x32_bf16 v[8:11], v[192:195], v[216:219], v[8:11]
	v_mfma_f32_16x16x32_bf16 v[4:7], v[184:187], v[224:227], v[4:7]
	v_mfma_f32_16x16x32_bf16 v[0:3], v[192:195], v[224:227], v[0:3]
	s_setprio 0
	s_barrier
; #define PG8_STAGE(bufoff, gbase, voff) do { _Pragma("unroll") for (int _i = 0; _i < 2; ++_i) \
;         __builtin_amdgcn_global_load_lds((const unsigned*)((const char*)(gbase) + (voff)[_i]), (LAS unsigned*)(lds + (bufoff) + ldsw + _i * 8192), 16, 0, 0); } while (0)
; #define PG8_LDA(dst, b, h) do { _Pragma("unroll") for (int m = 0; m < 4; ++m) _Pragma("unroll") for (int k = 0; k < 2; ++k) dst[m][k] = *(const LAS bf16x8*)(lds + PG8_SA(b, h) + aoff + m * 2048 + k * 1024); } while (0)
; #define PG8_LDB(dst, b, h) do { _Pragma("unroll") for (int n = 0; n < 2; ++n) _Pragma("unroll") for (int k = 0; k < 2; ++k) dst[n][k] = *(const LAS bf16x8*)(lds + PG8_SB(b, h) + boff + n * 2048 + k * 1024); } while (0)
; #define PG8_MMA(ai, bj, At, Bt) do { __builtin_amdgcn_s_setprio(1); _Pragma("unroll") for (int m = 0; m < 4; ++m) _Pragma("unroll") for (int n = 0; n < 2; ++n) _Pragma("unroll") for (int k = 0; k < 2; ++k) \
;         acc[ai][bj][m][n] = __builtin_amdgcn_mfma_f32_16x16x32_bf16(Bt[n][k], At[m][k], acc[ai][bj][m][n], 0, 0, 0); __builtin_amdgcn_s_setprio(0); } while (0)
; #define PG8_WAIT_V(n) asm volatile("s_waitcnt vmcnt(" #n ")" ::: "memory")
; #define PG8_WAIT_L(n) asm volatile("s_waitcnt lgkmcnt(" #n ")" ::: "memory")
; #define PG8_BAR __builtin_amdgcn_s_barrier()
; #define PG8_SCHED __builtin_amdgcn_sched_barrier(0)
; template <class Epi, class Sched, bool ALIGN_EPI, bool SP2>
; __device__ __forceinline__ void gemm_phase(LAS unsigned char* lds, const Gemm g, const Sched& S, const Epi& E) {
;     ...
;             PG8_LDB(B0, 1, 0); PG8_LDB(B1, 1, 1); PG8_SCHED; PG8_LDA(At, 1, 0); PG8_STAGE(PG8_SA(0, 1), a2 + hstep, voffA);
;             PG8_WAIT_V(8); PG8_WAIT_L(0); PG8_BAR; PG8_MMA(0, 0, At, B0); PG8_MMA(0, 1, At, B1); PG8_BAR; PG8_SCHED;
;             PG8_LDA(At, 1, 1); PG8_STAGE(PG8_SB(1, 0), b3, voffB); PG8_STAGE(PG8_SB(1, 1), b3 + hstep, voffB); PG8_STAGE(PG8_SA(1, 0), a3, voffA);
;             PG8_WAIT_V(8); PG8_WAIT_L(0); PG8_BAR; PG8_MMA(1, 0, At, B0); PG8_MMA(1, 1, At, B1); PG8_BAR; PG8_SCHED;
	s_add_i32 s44, 0, 0x18000
	s_add_i32 s45, 0, 0x1c000
	v_add_u32_e32 v140, s44, v174
	v_add_u32_e32 v152, s45, v174
	s_add_u32 s10, s10, 0x40000
	s_addc_u32 s11, s11, 0
	s_mov_b32 m0, s73
	s_nop 0
	global_load_lds_dwordx4 v144, s[10:11]
	s_mov_b32 m0, s82
	s_nop 0
	global_load_lds_dwordx4 v148, s[10:11]
	ds_read_b128 v[128:131], v140
	ds_read_b128 v[132:135], v140 offset:1024
	ds_read_b128 v[136:139], v140 offset:2048
	ds_read_b128 v[140:143], v140 offset:3072
	ds_read_b128 v[168:171], v152
	ds_read_b128 v[184:187], v152 offset:1024
	ds_read_b128 v[188:191], v152 offset:2048
	ds_read_b128 v[192:195], v152 offset:3072
	ds_read_b128 v[196:199], v179 offset:32768
	ds_read_b128 v[200:203], v179 offset:33792
	ds_read_b128 v[204:207], v179 offset:34816
	ds_read_b128 v[208:211], v179 offset:35840
	ds_read_b128 v[212:215], v179 offset:36864
	ds_read_b128 v[216:219], v179 offset:37888
	ds_read_b128 v[220:223], v179 offset:38912
	ds_read_b128 v[224:227], v179 offset:39936
	s_waitcnt vmcnt(8)
	s_waitcnt lgkmcnt(0)
	s_barrier
	s_setprio 1
	s_waitcnt lgkmcnt(0)
	v_mfma_f32_16x16x32_bf16 v[124:127], v[128:131], v[196:199], v[124:127]
	v_mfma_f32_16x16x32_bf16 v[120:123], v[136:139], v[196:199], v[120:123]
	v_mfma_f32_16x16x32_bf16 v[116:119], v[128:131], v[204:207], v[116:119]
	v_mfma_f32_16x16x32_bf16 v[112:115], v[136:139], v[204:207], v[112:115]
	v_mfma_f32_16x16x32_bf16 v[108:111], v[128:131], v[212:215], v[108:111]
	v_mfma_f32_16x16x32_bf16 v[104:107], v[136:139], v[212:215], v[104:107]
	v_mfma_f32_16x16x32_bf16 v[100:103], v[128:131], v[220:223], v[100:103]
	v_mfma_f32_16x16x32_bf16 v[96:99], v[136:139], v[220:223], v[96:99]
	v_mfma_f32_16x16x32_bf16 v[124:127], v[132:135], v[200:203], v[124:127]
	v_mfma_f32_16x16x32_bf16 v[120:123], v[140:143], v[200:203], v[120:123]
	v_mfma_f32_16x16x32_bf16 v[116:119], v[132:135], v[208:211], v[116:119]
	v_mfma_f32_16x16x32_bf16 v[112:115], v[140:143], v[208:211], v[112:115]
	v_mfma_f32_16x16x32_bf16 v[108:111], v[132:135], v[216:219], v[108:111]
	v_mfma_f32_16x16x32_bf16 v[104:107], v[140:143], v[216:219], v[104:107]
	v_mfma_f32_16x16x32_bf16 v[100:103], v[132:135], v[224:227], v[100:103]
	v_mfma_f32_16x16x32_bf16 v[96:99], v[140:143], v[224:227], v[96:99]
	s_setprio 0
	s_setprio 1
	v_mfma_f32_16x16x32_bf16 v[60:63], v[168:171], v[196:199], v[60:63]
	v_mfma_f32_16x16x32_bf16 v[56:59], v[188:191], v[196:199], v[56:59]
	v_mfma_f32_16x16x32_bf16 v[52:55], v[168:171], v[204:207], v[52:55]
	v_mfma_f32_16x16x32_bf16 v[48:51], v[188:191], v[204:207], v[48:51]
	v_mfma_f32_16x16x32_bf16 v[44:47], v[168:171], v[212:215], v[44:47]
	v_mfma_f32_16x16x32_bf16 v[40:43], v[188:191], v[212:215], v[40:43]
	v_mfma_f32_16x16x32_bf16 v[36:39], v[168:171], v[220:223], v[36:39]
	v_mfma_f32_16x16x32_bf16 v[32:35], v[188:191], v[220:223], v[32:35]
	v_mfma_f32_16x16x32_bf16 v[60:63], v[184:187], v[200:203], v[60:63]
	v_mfma_f32_16x16x32_bf16 v[56:59], v[192:195], v[200:203], v[56:59]
	v_mfma_f32_16x16x32_bf16 v[52:55], v[184:187], v[208:211], v[52:55]
	v_mfma_f32_16x16x32_bf16 v[48:51], v[192:195], v[208:211], v[48:51]
	v_mfma_f32_16x16x32_bf16 v[44:47], v[184:187], v[216:219], v[44:47]
	v_mfma_f32_16x16x32_bf16 v[40:43], v[192:195], v[216:219], v[40:43]
	v_mfma_f32_16x16x32_bf16 v[36:39], v[184:187], v[224:227], v[36:39]
	v_mfma_f32_16x16x32_bf16 v[32:35], v[192:195], v[224:227], v[32:35]
	s_setprio 0
	s_barrier
	s_add_u32 s100, s10, 0xfffc0080
	s_addc_u32 s101, s11, -1
	s_add_u32 s98, s8, 0x80
	s_addc_u32 s99, s9, 0
	s_add_i32 s10, s44, s70
	s_mov_b32 m0, s10
	s_nop 0
	global_load_lds_dwordx4 v146, s[98:99]
	s_add_i32 m0, s10, 0x2000
	s_add_u32 s8, s8, 0x40080
	s_addc_u32 s9, s9, 0
	s_add_i32 s10, s45, s70
	global_load_lds_dwordx4 v150, s[98:99]
	s_mov_b32 m0, s10
	s_nop 0
	global_load_lds_dwordx4 v146, s[8:9]
	s_add_i32 m0, s10, 0x2000
	s_nop 0
	global_load_lds_dwordx4 v150, s[8:9]
	s_mov_b32 m0, s83
	s_nop 0
	global_load_lds_dwordx4 v144, s[100:101]
	s_mov_b32 m0, s84
	s_nop 0
	global_load_lds_dwordx4 v148, s[100:101]
	ds_read_b128 v[196:199], v179 offset:49152
	ds_read_b128 v[200:203], v179 offset:50176
	ds_read_b128 v[204:207], v179 offset:51200
	ds_read_b128 v[208:211], v179 offset:52224
	ds_read_b128 v[212:215], v179 offset:53248
	ds_read_b128 v[216:219], v179 offset:54272
	ds_read_b128 v[220:223], v179 offset:55296
	ds_read_b128 v[224:227], v179 offset:56320
	s_waitcnt vmcnt(8)
	s_waitcnt lgkmcnt(0)
	s_barrier
	s_setprio 1
	s_waitcnt lgkmcnt(0)
	v_mfma_f32_16x16x32_bf16 v[92:95], v[128:131], v[196:199], v[92:95]
	v_mfma_f32_16x16x32_bf16 v[88:91], v[136:139], v[196:199], v[88:91]
	v_mfma_f32_16x16x32_bf16 v[84:87], v[128:131], v[204:207], v[84:87]
	v_mfma_f32_16x16x32_bf16 v[80:83], v[136:139], v[204:207], v[80:83]
	v_mfma_f32_16x16x32_bf16 v[76:79], v[128:131], v[212:215], v[76:79]
	v_mfma_f32_16x16x32_bf16 v[72:75], v[136:139], v[212:215], v[72:75]
	v_mfma_f32_16x16x32_bf16 v[68:71], v[128:131], v[220:223], v[68:71]
	v_mfma_f32_16x16x32_bf16 v[64:67], v[136:139], v[220:223], v[64:67]
	v_mfma_f32_16x16x32_bf16 v[92:95], v[132:135], v[200:203], v[92:95]
	v_mfma_f32_16x16x32_bf16 v[88:91], v[140:143], v[200:203], v[88:91]
	v_mfma_f32_16x16x32_bf16 v[84:87], v[132:135], v[208:211], v[84:87]
	v_mfma_f32_16x16x32_bf16 v[80:83], v[140:143], v[208:211], v[80:83]
	v_mfma_f32_16x16x32_bf16 v[76:79], v[132:135], v[216:219], v[76:79]
	v_mfma_f32_16x16x32_bf16 v[72:75], v[140:143], v[216:219], v[72:75]
	v_mfma_f32_16x16x32_bf16 v[68:71], v[132:135], v[224:227], v[68:71]
	v_mfma_f32_16x16x32_bf16 v[64:67], v[140:143], v[224:227], v[64:67]
	s_setprio 0
	s_setprio 1
	v_mfma_f32_16x16x32_bf16 v[28:31], v[168:171], v[196:199], v[28:31]
	v_mfma_f32_16x16x32_bf16 v[24:27], v[188:191], v[196:199], v[24:27]
	v_mfma_f32_16x16x32_bf16 v[20:23], v[168:171], v[204:207], v[20:23]
	v_mfma_f32_16x16x32_bf16 v[16:19], v[188:191], v[204:207], v[16:19]
	v_mfma_f32_16x16x32_bf16 v[12:15], v[168:171], v[212:215], v[12:15]
	v_mfma_f32_16x16x32_bf16 v[8:11], v[188:191], v[212:215], v[8:11]
	v_mfma_f32_16x16x32_bf16 v[4:7], v[168:171], v[220:223], v[4:7]
	v_mfma_f32_16x16x32_bf16 v[0:3], v[188:191], v[220:223], v[0:3]
	v_mfma_f32_16x16x32_bf16 v[28:31], v[184:187], v[200:203], v[28:31]
	v_mfma_f32_16x16x32_bf16 v[24:27], v[192:195], v[200:203], v[24:27]
	v_mfma_f32_16x16x32_bf16 v[20:23], v[184:187], v[208:211], v[20:23]
	v_mfma_f32_16x16x32_bf16 v[16:19], v[192:195], v[208:211], v[16:19]
	v_mfma_f32_16x16x32_bf16 v[12:15], v[184:187], v[216:219], v[12:15]
	v_mfma_f32_16x16x32_bf16 v[8:11], v[192:195], v[216:219], v[8:11]
	v_mfma_f32_16x16x32_bf16 v[4:7], v[184:187], v[224:227], v[4:7]
	v_mfma_f32_16x16x32_bf16 v[0:3], v[192:195], v[224:227], v[0:3]
	s_setprio 0
	s_barrier
	s_add_i32 s43, s43, 2
	s_add_u32 s6, s6, 0x100
	s_addc_u32 s7, s7, 0
	s_add_u32 s13, s13, 0x100
	s_addc_u32 s42, s42, 0
	s_cmp_gt_u32 s43, 13
	s_cbranch_scc0 .LBB0_216
	s_and_b64 vcc, exec, s[34:35]
	s_cbranch_vccnz .LBB0_221
	v_lshl_add_u32 v168, s4, 8, v155
	s_cmp_lg_u32 s16, 2
	s_mov_b64 s[4:5], -1
	s_cbranch_scc1 .LBB0_222
